# P2 work queue: next item index fetched (atomicAdd) by thread 0 while the current bulk item runs
# baseline (speedup 1.0000x reference)
; __global__ void __launch_bounds__(NTHR) fwd_mega(Params p, int ph_lo, int ph_hi) {
;   cg::grid_group grid = cg::this_grid();
;   if (threadIdx.x < 2) *reinterpret_cast<volatile unsigned*>(smem + LDS_BYTES - 32 + 4 * threadIdx.x) = 0u;
;   __syncthreads();
_Z8fwd_mega6Paramsii:
	s_mov_b32 s98, 0
	s_load_dwordx2 s[66:67], s[0:1], 0x118
	s_mov_b32 s65, s2
	s_add_u32 s2, s0, 0x118
	s_addc_u32 s3, s1, 0
	v_mov_b32_e32 v1, 0
	v_writelane_b32 v248, s0, 0
	s_waitcnt lgkmcnt(0)
	s_cmp_lt_u32 s65, s66
	v_and_b32_e32 v188, 0x3ff, v0
	v_writelane_b32 v248, s1, 1
	v_cmp_gt_u32_e32 vcc, 2, v188
	global_load_dword v2, v1, s[0:1] offset:294
	s_cselect_b32 s0, 12, 18
	s_add_u32 s0, s2, s0
	v_writelane_b32 v248, s2, 2
	s_addc_u32 s1, s3, 0
	global_load_ushort v3, v1, s[0:1]
	v_writelane_b32 v248, s3, 3
	s_waitcnt vmcnt(1)
	v_readfirstlane_b32 s33, v2
	s_waitcnt vmcnt(0)
	v_readfirstlane_b32 s54, v3
	s_and_saveexec_b64 s[0:1], vcc
	s_cbranch_execz .LBB0_2
	s_mov_b64 s[2:3], src_shared_base
	s_mov_b32 s2, 0x200e0
	s_addk_i32 s2, 0x100
	v_lshl_add_u32 v2, v188, 2, s2
	v_mov_b32_e32 v3, s3
	flat_store_dword v[2:3], v1 sc0 sc1
	s_waitcnt vmcnt(0)

; __device__ __forceinline__ void phase_p2(const Params& p, int l) {
;     ...
;   while (true) {
;     if (threadIdx.x == 0) *s_item = atomicAdd(p.ctr + l, 1);
;     __syncthreads();
.LBB0_349:
	s_and_saveexec_b64 s[0:1], s[70:71]
	s_cbranch_execz .LBB0_353
	s_cmp_lg_u32 s98, 0
	s_cbranch_scc0 .Ldq_fresh
	s_waitcnt vmcnt(0)
	v_mov_b32_e32 v0, v245
	v_readlane_b32 s2, v247, 35
	s_nop 1
	v_mov_b32_e32 v1, s2
	ds_write_b32 v1, v0
	s_branch .LBB0_353
.Ldq_fresh:
	s_mov_b64 s[2:3], exec
	v_mbcnt_lo_u32_b32 v0, s2, 0
	v_mbcnt_hi_u32_b32 v0, s3, v0
	v_cmp_eq_u32_e32 vcc, 0, v0
	s_and_saveexec_b64 s[4:5], vcc
	s_cbranch_execz .LBB0_352
	s_bcnt1_i32_b64 s2, s[2:3]
	v_mov_b32_e32 v1, s2
	v_readlane_b32 s2, v246, 13
	v_readlane_b32 s3, v246, 14
	s_nop 4
	global_atomic_add v1, v191, v1, s[2:3] sc0

; __device__ __forceinline__ void phase_p2(const Params& p, int l) {
;     ...
;     if (threadIdx.x == 0) *s_item = atomicAdd(p.ctr + l, 1);
;     __syncthreads();
;     const int item = *s_item;
;     __syncthreads();
;     if (item >= Q_CVP) break;
.LBB0_353:
	s_mov_b32 s98, 0
	s_mov_b32 s95, 0x1c000
	s_mov_b32 s94, 0x18000
	s_mov_b32 s91, 0x14000
	s_mov_b32 s90, 0x10000
	s_or_b64 exec, exec, s[0:1]
	v_readlane_b32 s0, v247, 35
	s_waitcnt lgkmcnt(0)
	s_barrier
	v_mov_b32_e32 v0, s0
	ds_read_b32 v0, v0
	s_movk_i32 s0, 0xb49
	s_waitcnt lgkmcnt(0)
	s_barrier
	v_cmp_lt_i32_e32 vcc, s0, v0
	v_readfirstlane_b32 s89, v0
	s_mov_b64 s[0:1], -1
	s_cbranch_vccnz .LBB0_348
	s_cmpk_lt_i32 s89, 0x14a
	s_cbranch_scc1 .Ldq_nopf
	s_mov_b32 s98, 1
	s_and_saveexec_b64 s[2:3], s[70:71]
	s_cbranch_execz .Ldq_pf_skip
	v_readlane_b32 s4, v246, 13
	v_readlane_b32 s5, v246, 14
	v_mov_b32_e32 v245, 1
	s_nop 4
	global_atomic_add v245, v191, v245, s[4:5] sc0

; __device__ __forceinline__ void phase_p2(const Params& p, int l) {
;     ...
;     int kind, sub;
;     if (item < Q_HGP) { kind = 0; sub = item; }
;     else if (item < Q_HGS) { kind = 0; sub = 128 + item - Q_HGP; }
;     else if (item < Q_ATS) { kind = 1; sub = 2048 + item - Q_HGS; }
;     else if (item < Q_CVS) { kind = 2; sub = 512 + item - Q_ATS; }
;     else if (item < Q_P3S) { kind = 3; sub = item - Q_CVS; }
;     else if (item < Q_P4S) { kind = 4; sub = item - Q_P3S; }
;     else if (item < Q_ATP) { kind = 1; sub = item - Q_P4S; }
;     else { kind = 2; sub = item - Q_ATP; }
.Ldq_nopf:
	s_cmpk_gt_i32 s89, 0xbf
	s_mov_b64 s[2:3], 0
	s_mov_b64 s[6:7], 0
	s_cselect_b64 s[0:1], -1, 0
	s_cmpk_lt_i32 s89, 0xc0
	s_mov_b64 s[4:5], 0
	v_writelane_b32 v246, s2, 33
	s_mov_b32 s46, s89
	s_nop 0
	v_writelane_b32 v246, s3, 34
	s_cbranch_scc1 .LBB0_373
	s_cmpk_gt_u32 s89, 0x13f
	s_mov_b64 s[8:9], -1
	s_cbranch_scc0 .LBB0_371
	s_cmpk_gt_u32 s89, 0x141
	s_cbranch_scc0 .LBB0_368
	s_cmpk_gt_u32 s89, 0x145
	s_mov_b64 s[10:11], -1
	s_cbranch_scc0 .LBB0_366
	s_cmpk_gt_u32 s89, 0x149
	s_cbranch_scc0 .LBB0_363
	s_mov_b64 s[4:5], -1
	s_cmpk_gt_u32 s89, 0x949
	s_mov_b64 s[6:7], -1
	s_cbranch_scc0 .LBB0_361
	s_add_i32 s46, s89, 0xfffff6b6
	s_mov_b64 s[6:7], 0

; __device__ __forceinline__ void phase_p2(const Params& p, int l) {
;   int* s_item = reinterpret_cast<int*>(smem + LDS_BYTES - 16);
;   int* cnt_s = p.ctr + 2 + l; int* cnt_m = p.ctr + 4 + l;
;   while (true) {
;     if (threadIdx.x == 0) *s_item = atomicAdd(p.ctr + l, 1);
;     __syncthreads();
;     const int item = *s_item;
;     __syncthreads();
;     if (item >= Q_CVP) break;
	.amdhsa_kernel _Z8fwd_mega6Paramsii
		.amdhsa_group_segment_fixed_size 256
		.amdhsa_private_segment_fixed_size 0
		.amdhsa_kernarg_size 536
		.amdhsa_user_sgpr_count 2
		.amdhsa_user_sgpr_dispatch_ptr 0
		.amdhsa_user_sgpr_queue_ptr 0
		.amdhsa_user_sgpr_kernarg_segment_ptr 1
		.amdhsa_user_sgpr_dispatch_id 0
		.amdhsa_user_sgpr_kernarg_preload_length 0
		.amdhsa_user_sgpr_kernarg_preload_offset 0
		.amdhsa_user_sgpr_private_segment_size 0
		.amdhsa_uses_dynamic_stack 0
		.amdhsa_enable_private_segment 0
		.amdhsa_system_sgpr_workgroup_id_x 1
		.amdhsa_system_sgpr_workgroup_id_y 0
		.amdhsa_system_sgpr_workgroup_id_z 0
		.amdhsa_system_sgpr_workgroup_info 0
		.amdhsa_system_vgpr_workitem_id 2
		.amdhsa_next_free_vgpr 252
		.amdhsa_next_free_sgpr 100
		.amdhsa_accum_offset 252
		.amdhsa_reserve_vcc 1
		.amdhsa_float_round_mode_32 0
		.amdhsa_float_round_mode_16_64 0
		.amdhsa_float_denorm_mode_32 3
		.amdhsa_float_denorm_mode_16_64 3
		.amdhsa_dx10_clamp 1
		.amdhsa_ieee_mode 1
		.amdhsa_fp16_overflow 0
		.amdhsa_tg_split 0
		.amdhsa_exception_fp_ieee_invalid_op 0
		.amdhsa_exception_fp_denorm_src 0
		.amdhsa_exception_fp_ieee_div_zero 0
		.amdhsa_exception_fp_ieee_overflow 0
		.amdhsa_exception_fp_ieee_underflow 0
		.amdhsa_exception_fp_ieee_inexact 0
		.amdhsa_exception_int_div_zero 0
	.end_amdhsa_kernel

; __device__ __forceinline__ void phase_p2(const Params& p, int l) {
;   int* s_item = reinterpret_cast<int*>(smem + LDS_BYTES - 16);
;   int* cnt_s = p.ctr + 2 + l; int* cnt_m = p.ctr + 4 + l;
;   while (true) {
;     if (threadIdx.x == 0) *s_item = atomicAdd(p.ctr + l, 1);
;     __syncthreads();
;     const int item = *s_item;
;     __syncthreads();
;     if (item >= Q_CVP) break;
amdhsa.kernels:
  - .agpr_count:     0
    .args:
      - .offset:         0
        .size:           272
        .value_kind:     by_value
      - .offset:         272
        .size:           4
        .value_kind:     by_value
      - .offset:         276
        .size:           4
        .value_kind:     by_value
      - .offset:         280
        .size:           4
        .value_kind:     hidden_block_count_x
      - .offset:         284
        .size:           4
        .value_kind:     hidden_block_count_y
      - .offset:         288
        .size:           4
        .value_kind:     hidden_block_count_z
      - .offset:         292
        .size:           2
        .value_kind:     hidden_group_size_x
      - .offset:         294
        .size:           2
        .value_kind:     hidden_group_size_y
      - .offset:         296
        .size:           2
        .value_kind:     hidden_group_size_z
      - .offset:         298
        .size:           2
        .value_kind:     hidden_remainder_x
      - .offset:         300
        .size:           2
        .value_kind:     hidden_remainder_y
      - .offset:         302
        .size:           2
        .value_kind:     hidden_remainder_z
      - .offset:         320
        .size:           8
        .value_kind:     hidden_global_offset_x
      - .offset:         328
        .size:           8
        .value_kind:     hidden_global_offset_y
      - .offset:         336
        .size:           8
        .value_kind:     hidden_global_offset_z
      - .offset:         344
        .size:           2
        .value_kind:     hidden_grid_dims
      - .offset:         368
        .size:           8
        .value_kind:     hidden_multigrid_sync_arg
      - .offset:         400
        .size:           4
        .value_kind:     hidden_dynamic_lds_size
    .group_segment_fixed_size: 256
    .kernarg_segment_align: 8
    .kernarg_segment_size: 536
    .language:       OpenCL C
    .language_version:
      - 2
      - 0
    .max_flat_workgroup_size: 512
    .name:           _Z8fwd_mega6Paramsii
    .private_segment_fixed_size: 0
    .sgpr_count:     106
    .sgpr_spill_count: 181
    .symbol:         _Z8fwd_mega6Paramsii.kd
    .uniform_work_group_size: 1
    .uses_dynamic_stack: false
    .vgpr_count:     252
    .vgpr_spill_count: 0
    .wavefront_size: 64
